# attention loop QK sections: finishSM VALU (exp/sum/pack/permlane) spread over all MFMA gaps instead of piling up behind the last MFMA; 8+4 temps renamed off the K-fragment registers
# baseline (speedup 1.0000x reference)
; __device__ __forceinline__ void finishSM(f32x16& p0, f32x16& p1, float alpha, float& l_reg, bf16x8& pa0, bf16x8& pa1, bf16x8& pa2, bf16x8& pa3) {
;     for (int r = 0; r < 16; ++r) p1[r] = __builtin_amdgcn_exp2f(p1[r]);
;     float ps = 0; for (int r = 0; r < 16; ++r) ps += p0[r]; for (int r = 0; r < 16; ++r) ps += p1[r];
;     { auto rr = __builtin_amdgcn_permlane32_swap(__float_as_uint(ps), __float_as_uint(ps), false, false);
;       ps = __uint_as_float(rr[0]) + __uint_as_float(rr[1]); }
;     l_reg = l_reg * alpha + ps;
;     ...
;     PK4(p0, 0, pa0); PK4(p0, 8, pa1); PK4(p1, 0, pa2); PK4(p1, 8, pa3);
;     ...
; }
; template <int KB>
; __device__ __forceinline__ void qkt(f32x16& p0, f32x16& p1, const char* K_lds, int r32, int hi, const bf16x8* qr) {
;     p0 = f32x16{}; p1 = f32x16{};
;     const char* kb[4];
; #pragma unroll
;     for (int dd = 0; dd < 4; ++dd) kb[dd] = K_lds + KB * SHM_K + KSWZ(r32, (dd * 16 + hi * 8) * 2);
; #pragma unroll
;     for (int d0 = 0; d0 < 8; ++d0) { const char* a = kb[d0 & 3] + (d0 >> 2) * 128;
;         bf16x8 b0 = *reinterpret_cast<const bf16x8*>(a);
;         bf16x8 b1 = *reinterpret_cast<const bf16x8*>(a + 32 * 256);
;         p0 = __builtin_amdgcn_mfma_f32_32x32x16_bf16(b0, qr[d0], p0, 0, 0, 0);
;         p1 = __builtin_amdgcn_mfma_f32_32x32x16_bf16(b1, qr[d0], p1, 0, 0, 0); }
; }
.LBB0_89:
	s_waitcnt vmcnt(0)
	ds_read_b128 v[66:69], v169 offset:49152
	ds_read_b128 v[70:73], v169 offset:57344
	ds_read_b128 v[100:103], v193 offset:49152
	ds_read_b128 v[136:139], v193 offset:57344
	s_waitcnt lgkmcnt(3)
	v_mfma_f32_32x32x16_bf16 v[82:97], v[66:69], v[132:135], 0
	v_add_f32_e32 v148, 0, v231
	v_add_f32_e32 v148, v233, v148
	v_add_f32_e32 v148, v229, v148
	v_add_f32_e32 v148, v232, v148
	v_add_f32_e32 v148, v228, v148
	s_waitcnt lgkmcnt(2)
	v_mfma_f32_32x32x16_bf16 v[66:81], v[70:73], v[132:135], 0
	v_add_f32_e32 v148, v230, v148
	v_add_f32_e32 v148, v226, v148
	v_add_f32_e32 v148, v227, v148
	v_add_f32_e32 v148, v223, v148
	v_add_f32_e32 v148, v225, v148
	s_waitcnt lgkmcnt(1)
	v_mfma_f32_32x32x16_bf16 v[82:97], v[100:103], v[128:131], v[82:97]
	v_add_f32_e32 v148, v209, v148
	v_add_f32_e32 v148, v224, v148
	v_add_f32_e32 v148, v206, v148
	v_add_f32_e32 v148, v208, v148
	v_add_f32_e32 v148, v205, v148
	s_waitcnt lgkmcnt(0)
	v_mfma_f32_32x32x16_bf16 v[66:81], v[136:139], v[128:131], v[66:81]
	v_add_f32_e32 v148, v207, v148
	v_exp_f32_e32 v140, v152
	v_exp_f32_e32 v141, v153
	v_exp_f32_e32 v142, v180
	v_exp_f32_e32 v143, v181
	ds_read_b128 v[100:103], v194 offset:49152
	ds_read_b128 v[136:139], v194 offset:57344
	s_waitcnt lgkmcnt(1)
	v_mfma_f32_32x32x16_bf16 v[82:97], v[100:103], v[124:127], v[82:97]
	v_exp_f32_e32 v144, v160
	v_exp_f32_e32 v145, v161
	v_exp_f32_e32 v146, v154
	v_exp_f32_e32 v147, v155
	v_exp_f32_e32 v234, v178
	s_waitcnt lgkmcnt(0)
	v_mfma_f32_32x32x16_bf16 v[66:81], v[136:139], v[124:127], v[66:81]
	v_exp_f32_e32 v235, v179
	v_exp_f32_e32 v236, v162
	v_exp_f32_e32 v237, v163
	v_add_f32_e32 v148, v234, v148
	v_add_f32_e32 v148, v235, v148
	ds_read_b128 v[100:103], v195 offset:49152
	ds_read_b128 v[136:139], v195 offset:57344
	s_waitcnt lgkmcnt(1)
	v_mfma_f32_32x32x16_bf16 v[82:97], v[100:103], v[120:123], v[82:97]
	v_add_f32_e32 v148, v236, v148
	v_exp_f32_e32 v238, v158
	v_exp_f32_e32 v239, v159
	v_exp_f32_e32 v240, v156
	v_exp_f32_e32 v241, v157
	s_waitcnt lgkmcnt(0)
	v_mfma_f32_32x32x16_bf16 v[66:81], v[136:139], v[120:123], v[66:81]
	v_add_f32_e32 v148, v237, v148
	v_add_f32_e32 v148, v238, v148
	v_add_f32_e32 v148, v239, v148
	v_add_f32_e32 v148, v240, v148
	v_add_f32_e32 v148, v241, v148
	ds_read_b128 v[100:103], v169 offset:49280
	ds_read_b128 v[136:139], v169 offset:57472
	s_waitcnt lgkmcnt(1)
	v_mfma_f32_32x32x16_bf16 v[82:97], v[100:103], v[116:119], v[82:97]
	v_add_f32_e32 v148, v140, v148
	v_add_f32_e32 v148, v141, v148
	v_add_f32_e32 v148, v142, v148
	v_add_f32_e32 v148, v143, v148
	v_add_f32_e32 v148, v144, v148
	s_waitcnt lgkmcnt(0)
	v_mfma_f32_32x32x16_bf16 v[66:81], v[136:139], v[116:119], v[66:81]
	v_add_f32_e32 v148, v145, v148
	v_add_f32_e32 v148, v146, v148
	v_add_f32_e32 v199, v147, v148
	v_mov_b32_e32 v200, v199
	s_nop 1
	v_permlane32_swap_b32_e32 v199, v200
	v_cvt_pk_bf16_f32 v148, v231, v233
	ds_read_b128 v[100:103], v193 offset:49280
	ds_read_b128 v[136:139], v193 offset:57472
	s_waitcnt lgkmcnt(1)
	v_mfma_f32_32x32x16_bf16 v[82:97], v[100:103], v[112:115], v[82:97]
	v_cvt_pk_bf16_f32 v149, v229, v232
	v_cvt_pk_bf16_f32 v150, v228, v230
	v_cvt_pk_bf16_f32 v151, v226, v227
	v_cvt_pk_bf16_f32 v152, v223, v225
	v_cvt_pk_bf16_f32 v153, v209, v224
	s_waitcnt lgkmcnt(0)
	v_mfma_f32_32x32x16_bf16 v[66:81], v[136:139], v[112:115], v[66:81]
	v_cvt_pk_bf16_f32 v154, v206, v208
	v_cvt_pk_bf16_f32 v155, v205, v207
	v_cvt_pk_bf16_f32 v156, v234, v235
	v_cvt_pk_bf16_f32 v157, v236, v237
	v_cvt_pk_bf16_f32 v158, v238, v239
	ds_read_b128 v[100:103], v194 offset:49280
	ds_read_b128 v[136:139], v194 offset:57472
	s_waitcnt lgkmcnt(1)
	v_mfma_f32_32x32x16_bf16 v[82:97], v[100:103], v[108:111], v[82:97]
	v_cvt_pk_bf16_f32 v159, v240, v241
	v_cvt_pk_bf16_f32 v160, v140, v141
	v_cvt_pk_bf16_f32 v161, v142, v143
	v_cvt_pk_bf16_f32 v162, v144, v145
	v_cvt_pk_bf16_f32 v163, v146, v147
	s_waitcnt lgkmcnt(0)
	v_mfma_f32_32x32x16_bf16 v[66:81], v[136:139], v[108:111], v[66:81]
	s_nop 0
	v_permlane32_swap_b32_e32 v148, v150
	v_permlane32_swap_b32_e32 v149, v151
	v_permlane32_swap_b32_e32 v152, v154
	v_permlane32_swap_b32_e32 v153, v155
	ds_read_b128 v[100:103], v195 offset:49280
	ds_read_b128 v[136:139], v195 offset:57472
	s_waitcnt lgkmcnt(1)
	v_mfma_f32_32x32x16_bf16 v[82:97], v[100:103], v[104:107], v[82:97]
	v_permlane32_swap_b32_e32 v156, v158
	v_permlane32_swap_b32_e32 v157, v159
	v_permlane32_swap_b32_e32 v160, v162
	v_permlane32_swap_b32_e32 v161, v163
	s_waitcnt lgkmcnt(0)
	v_mfma_f32_32x32x16_bf16 v[66:81], v[136:139], v[104:107], v[66:81]
	v_add_u32_e32 v178, s7, v166
	v_add_u32_e32 v100, 1, v178
	v_add_u32_e32 v102, 33, v178
	v_ashrrev_i32_e32 v101, 31, v100
	v_ashrrev_i32_e32 v103, 31, v102
	v_lshlrev_b64 v[140:141], 8, v[100:101]
	v_lshlrev_b64 v[142:143], 8, v[102:103]
	v_lshl_add_u64 v[100:101], v[170:171], 0, v[140:141]
	v_lshl_add_u64 v[136:137], v[170:171], 0, v[142:143]
	v_lshl_add_u64 v[140:141], v[176:177], 0, v[140:141]
	v_lshl_add_u64 v[144:145], v[176:177], 0, v[142:143]
	global_load_dwordx4 v[100:103], v[100:101], off
	s_nop 0
	global_load_dwordx4 v[136:139], v[136:137], off
	s_nop 0
	global_load_dwordx4 v[140:143], v[140:141], off
	s_nop 0
	global_load_dwordx4 v[144:147], v[144:145], off
	ds_read_b64_tr_b16 v[172:173], v185 offset:0
	ds_read_b64_tr_b16 v[174:175], v185 offset:0x800
	ds_read_b64_tr_b16 v[202:203], v185 offset:0x1000
	ds_read_b64_tr_b16 v[204:205], v185 offset:0x1800
	ds_read_b64_tr_b16 v[206:207], v185 offset:0x2000
	ds_read_b64_tr_b16 v[208:209], v185 offset:0x2800
	ds_read_b64_tr_b16 v[224:225], v185 offset:0x3000
	ds_read_b64_tr_b16 v[226:227], v185 offset:0x3800
	s_waitcnt lgkmcnt(0)
; __device__ __forceinline__ void mask_tile(f32x16& p0, f32x16& p1, int dq, unsigned W) {
;     const float NEG = -__builtin_inff();
; #pragma unroll
;     for (int r = 0; r < 16; ++r) {
;         const int c = (r & 3) + 8 * (r >> 2);
;         if ((unsigned)(dq - c) >= W) p0[r] = NEG;
;         if ((unsigned)(dq - c - 32) >= W) p1[r] = NEG;
;     }
; }
; template <int VB>
; __device__ __forceinline__ void pv_tile(f32x16* o, int vb0, bf16x8 pa0, bf16x8 pa1, bf16x8 pa2, bf16x8 pa3) {
;     ...
;     PV_D0(0); PV_D0(1); PV_D0(2); PV_D0(3);
	s_nop 0
	v_mfma_f32_32x32x16_bf16 v[50:65], v[148:151], v[172:175], v[50:65]
	ds_read_b64_tr_b16 v[172:173], v185 offset:0x200
	ds_read_b64_tr_b16 v[174:175], v185 offset:0xa00
	v_mfma_f32_32x32x16_bf16 v[50:65], v[152:155], v[202:205], v[50:65]
	ds_read_b64_tr_b16 v[202:203], v185 offset:0x1200
	ds_read_b64_tr_b16 v[204:205], v185 offset:0x1a00
	v_mfma_f32_32x32x16_bf16 v[50:65], v[156:159], v[206:209], v[50:65]
	ds_read_b64_tr_b16 v[206:207], v185 offset:0x2200
	ds_read_b64_tr_b16 v[208:209], v185 offset:0x2a00
	v_mfma_f32_32x32x16_bf16 v[50:65], v[160:163], v[224:227], v[50:65]
	ds_read_b64_tr_b16 v[224:225], v185 offset:0x3200
	ds_read_b64_tr_b16 v[226:227], v185 offset:0x3a00
	s_waitcnt lgkmcnt(0)
	v_mfma_f32_32x32x16_bf16 v[34:49], v[148:151], v[172:175], v[34:49]
	ds_read_b64_tr_b16 v[172:173], v185 offset:0x400
	ds_read_b64_tr_b16 v[174:175], v185 offset:0xc00
	v_mfma_f32_32x32x16_bf16 v[34:49], v[152:155], v[202:205], v[34:49]
	ds_read_b64_tr_b16 v[202:203], v185 offset:0x1400
	ds_read_b64_tr_b16 v[204:205], v185 offset:0x1c00
	v_mfma_f32_32x32x16_bf16 v[34:49], v[156:159], v[206:209], v[34:49]
	ds_read_b64_tr_b16 v[206:207], v185 offset:0x2400
	ds_read_b64_tr_b16 v[208:209], v185 offset:0x2c00
	v_mfma_f32_32x32x16_bf16 v[34:49], v[160:163], v[224:227], v[34:49]
	ds_read_b64_tr_b16 v[224:225], v185 offset:0x3400
	ds_read_b64_tr_b16 v[226:227], v185 offset:0x3c00
	s_waitcnt lgkmcnt(0)
	v_mfma_f32_32x32x16_bf16 v[18:33], v[148:151], v[172:175], v[18:33]
	ds_read_b64_tr_b16 v[172:173], v185 offset:0x600
	ds_read_b64_tr_b16 v[174:175], v185 offset:0xe00
	v_mfma_f32_32x32x16_bf16 v[18:33], v[152:155], v[202:205], v[18:33]
	ds_read_b64_tr_b16 v[202:203], v185 offset:0x1600
	ds_read_b64_tr_b16 v[204:205], v185 offset:0x1e00
	v_mfma_f32_32x32x16_bf16 v[18:33], v[156:159], v[206:209], v[18:33]
	ds_read_b64_tr_b16 v[206:207], v185 offset:0x2600
	ds_read_b64_tr_b16 v[208:209], v185 offset:0x2e00
	v_mfma_f32_32x32x16_bf16 v[18:33], v[160:163], v[224:227], v[18:33]
	ds_read_b64_tr_b16 v[224:225], v185 offset:0x3600
	ds_read_b64_tr_b16 v[226:227], v185 offset:0x3e00
	s_waitcnt lgkmcnt(0)
	v_mfma_f32_32x32x16_bf16 v[2:17], v[148:151], v[172:175], v[2:17]
	s_cmp_le_i32 s7, s6
	v_mfma_f32_32x32x16_bf16 v[2:17], v[152:155], v[202:205], v[2:17]
	v_mfma_f32_32x32x16_bf16 v[2:17], v[156:159], v[206:209], v[2:17]
	v_mfma_f32_32x32x16_bf16 v[2:17], v[160:163], v[224:227], v[2:17]
	s_cbranch_scc1 .LBB0_91
	v_add_u32_e32 v148, 0x4000007b, v197
	v_cmp_gt_u32_e32 vcc, 2.0, v148
	v_add_u32_e32 v148, 0x5b, v197
	s_nop 0
	v_cndmask_b32_e32 v82, v220, v82, vcc
	v_cmp_lt_u32_e32 vcc, s33, v148
	v_add_u32_e32 v148, 0x7a, v197
	s_nop 0
	v_cndmask_b32_e32 v66, v220, v66, vcc
	v_cmp_lt_u32_e32 vcc, s33, v148
	v_add_u32_e32 v148, 0x5a, v197
	s_nop 0
	v_cndmask_b32_e32 v83, v220, v83, vcc
	v_cmp_lt_u32_e32 vcc, s33, v148
	v_add_u32_e32 v148, 0x79, v197
	s_nop 0
	v_cndmask_b32_e32 v67, v220, v67, vcc
	v_cmp_lt_u32_e32 vcc, s33, v148
	v_add_u32_e32 v148, 0x59, v197
	s_nop 0
	v_cndmask_b32_e32 v84, v220, v84, vcc
	v_cmp_lt_u32_e32 vcc, s33, v148
	v_add_u32_e32 v148, 0x78, v197
	s_nop 0
	v_cndmask_b32_e32 v68, v220, v68, vcc
	v_cmp_lt_u32_e32 vcc, s33, v148
	v_add_u32_e32 v148, 0x58, v197
	s_nop 0
	v_cndmask_b32_e32 v85, v220, v85, vcc
	v_cmp_lt_u32_e32 vcc, s33, v148
	v_add_u32_e32 v148, 0x73, v197
	s_nop 0
	v_cndmask_b32_e32 v69, v220, v69, vcc
	v_cmp_lt_u32_e32 vcc, s33, v148
	v_add_u32_e32 v148, 0x53, v197
	s_nop 0
	v_cndmask_b32_e32 v86, v220, v86, vcc
	v_cmp_lt_u32_e32 vcc, s33, v148
	v_add_u32_e32 v148, 0x72, v197
	s_nop 0
	v_cndmask_b32_e32 v70, v220, v70, vcc
	v_cmp_lt_u32_e32 vcc, s33, v148
	v_add_u32_e32 v148, 0x52, v197
	s_nop 0
	v_cndmask_b32_e32 v87, v220, v87, vcc
	v_cmp_lt_u32_e32 vcc, s33, v148
	v_add_u32_e32 v148, 0x71, v197
	s_nop 0
	v_cndmask_b32_e32 v71, v220, v71, vcc
	v_cmp_lt_u32_e32 vcc, s33, v148
	v_add_u32_e32 v148, 0x51, v197
	s_nop 0
	v_cndmask_b32_e32 v88, v220, v88, vcc
	v_cmp_lt_u32_e32 vcc, s33, v148
	v_add_u32_e32 v148, 0x70, v197
	s_nop 0
	v_cndmask_b32_e32 v72, v220, v72, vcc
	v_cmp_lt_u32_e32 vcc, s33, v148
	v_add_u32_e32 v148, 0x50, v197
	s_nop 0
	v_cndmask_b32_e32 v89, v220, v89, vcc
	v_cmp_lt_u32_e32 vcc, s33, v148
	v_add_u32_e32 v148, 0x6b, v197
	s_nop 0
	v_cndmask_b32_e32 v73, v220, v73, vcc
	v_cmp_lt_u32_e32 vcc, s33, v148
	v_add_u32_e32 v148, 0x4b, v197
	s_nop 0
	v_cndmask_b32_e32 v90, v220, v90, vcc
	v_cmp_lt_u32_e32 vcc, s33, v148
	v_add_u32_e32 v148, 0x6a, v197
	s_nop 0
	v_cndmask_b32_e32 v74, v220, v74, vcc
	v_cmp_lt_u32_e32 vcc, s33, v148
	v_add_u32_e32 v148, 0x4a, v197
	s_nop 0
	v_cndmask_b32_e32 v91, v220, v91, vcc
	v_cmp_lt_u32_e32 vcc, s33, v148
	v_add_u32_e32 v148, 0x69, v197
	s_nop 0
	v_cndmask_b32_e32 v75, v220, v75, vcc
	v_cmp_lt_u32_e32 vcc, s33, v148
	v_add_u32_e32 v148, 0x49, v197
	s_nop 0
	v_cndmask_b32_e32 v92, v220, v92, vcc
	v_cmp_lt_u32_e32 vcc, s33, v148
	v_add_u32_e32 v148, 0x68, v197
	s_nop 0
	v_cndmask_b32_e32 v76, v220, v76, vcc
	v_cmp_lt_u32_e32 vcc, s33, v148
	v_add_u32_e32 v148, 0x48, v197
	s_nop 0
	v_cndmask_b32_e32 v93, v220, v93, vcc
	v_cmp_lt_u32_e32 vcc, s33, v148
	v_add_u32_e32 v148, 0x63, v197
	s_nop 0
	v_cndmask_b32_e32 v77, v220, v77, vcc
	v_cmp_lt_u32_e32 vcc, s33, v148
	v_add_u32_e32 v148, 0x43, v197
	s_nop 0
	v_cndmask_b32_e32 v94, v220, v94, vcc
	v_cmp_lt_u32_e32 vcc, s33, v148
	v_add_u32_e32 v148, 0x62, v197
	s_nop 0
	v_cndmask_b32_e32 v78, v220, v78, vcc
	v_cmp_lt_u32_e32 vcc, s33, v148
	v_add_u32_e32 v148, 0x42, v197
	s_nop 0
	v_cndmask_b32_e32 v95, v220, v95, vcc
	v_cmp_lt_u32_e32 vcc, s33, v148
	v_add_u32_e32 v148, 0x61, v197
	s_nop 0
	v_cndmask_b32_e32 v79, v220, v79, vcc
	v_cmp_lt_u32_e32 vcc, s33, v148
	v_add_u32_e32 v148, 0x41, v197
	s_nop 0
	v_cndmask_b32_e32 v96, v220, v96, vcc
	v_cmp_lt_u32_e32 vcc, s33, v148
	v_add_u32_e32 v148, 0x60, v197
	s_nop 0
	v_cndmask_b32_e32 v80, v220, v80, vcc
	v_cmp_lt_u32_e32 vcc, s33, v148
	v_add_u32_e32 v148, 64, v197
	s_nop 0
	v_cndmask_b32_e32 v97, v220, v97, vcc
	v_cmp_lt_u32_e32 vcc, s33, v148
	s_nop 1
	v_cndmask_b32_e32 v81, v220, v81, vcc

; __device__ __forceinline__ void partialSM(f32x16& p0, f32x16& p1, float& m_reg, float& mn, float& alpha, bool rs) {
;     ...
;     if (__builtin_expect(__all((pmax - m_reg) * SCALE <= THR), 1)) { mn = m_reg; alpha = 1.f; }
;     else { mn = fmaxf(m_reg, pmax); alpha = __builtin_amdgcn_exp2f((m_reg - mn) * C2); m_reg = mn; }
;     const float mnL = rs ? -mn * C2 : -__builtin_inff();
;     for (int r = 0; r < 16; ++r) p0[r] = fmaf(p0[r], C2, mnL); for (int r = 0; r < 16; ++r) p1[r] = fmaf(p1[r], C2, mnL);
;     for (int r = 0; r < 16; ++r) p0[r] = __builtin_amdgcn_exp2f(p0[r]);
.LBB0_95:
	v_cndmask_b32_e64 v179, v148, v198, s[42:43]
	v_mul_f32_e32 v148, 0xbe0293ee, v179
	v_cndmask_b32_e64 v180, v220, v148, s[40:41]
	v_fmamk_f32 v82, v82, 0x3e0293ee, v180
	v_fmamk_f32 v83, v83, 0x3e0293ee, v180
	v_fmamk_f32 v84, v84, 0x3e0293ee, v180
	v_fmamk_f32 v85, v85, 0x3e0293ee, v180
	v_fmamk_f32 v86, v86, 0x3e0293ee, v180
	v_fmamk_f32 v87, v87, 0x3e0293ee, v180
	v_fmamk_f32 v88, v88, 0x3e0293ee, v180
	v_fmamk_f32 v89, v89, 0x3e0293ee, v180
	v_fmamk_f32 v90, v90, 0x3e0293ee, v180
	v_fmamk_f32 v91, v91, 0x3e0293ee, v180
	v_fmamk_f32 v92, v92, 0x3e0293ee, v180
	v_fmamk_f32 v93, v93, 0x3e0293ee, v180
	v_fmamk_f32 v94, v94, 0x3e0293ee, v180
	v_fmamk_f32 v95, v95, 0x3e0293ee, v180
	v_fmamk_f32 v96, v96, 0x3e0293ee, v180
	v_fmamk_f32 v97, v97, 0x3e0293ee, v180
	v_exp_f32_e32 v148, v82
	v_exp_f32_e32 v163, v83
	v_exp_f32_e32 v149, v84
	v_exp_f32_e32 v162, v85
	v_exp_f32_e32 v150, v86
	v_exp_f32_e32 v161, v87
	v_exp_f32_e32 v151, v88
	v_exp_f32_e32 v160, v89
	v_exp_f32_e32 v152, v90
	v_exp_f32_e32 v159, v91
	v_exp_f32_e32 v153, v92
	v_exp_f32_e32 v158, v93
	v_exp_f32_e32 v154, v94
	v_exp_f32_e32 v157, v95
	v_exp_f32_e32 v155, v96
	v_exp_f32_e32 v156, v97
	v_fmamk_f32 v203, v73, 0x3e0293ee, v180
	v_fmamk_f32 v204, v74, 0x3e0293ee, v180
	v_fmamk_f32 v208, v66, 0x3e0293ee, v180
	v_fmamk_f32 v209, v67, 0x3e0293ee, v180
	v_fmamk_f32 v223, v68, 0x3e0293ee, v180
	v_fmamk_f32 v224, v69, 0x3e0293ee, v180
	v_fmamk_f32 v225, v70, 0x3e0293ee, v180
	v_fmamk_f32 v198, v71, 0x3e0293ee, v180
	v_fmamk_f32 v201, v72, 0x3e0293ee, v180
	v_fmamk_f32 v205, v75, 0x3e0293ee, v180
	v_fmamk_f32 v206, v76, 0x3e0293ee, v180
	v_fmamk_f32 v207, v77, 0x3e0293ee, v180
	v_fmamk_f32 v181, v78, 0x3e0293ee, v180
	v_fmamk_f32 v226, v79, 0x3e0293ee, v180
	v_fmamk_f32 v227, v80, 0x3e0293ee, v180
	v_fmac_f32_e32 v180, 0x3e0293ee, v81
	s_waitcnt lgkmcnt(0)
	s_barrier
; __device__ __forceinline__ void finishSM(f32x16& p0, f32x16& p1, float alpha, float& l_reg, bf16x8& pa0, bf16x8& pa1, bf16x8& pa2, bf16x8& pa3) {
;     for (int r = 0; r < 16; ++r) p1[r] = __builtin_amdgcn_exp2f(p1[r]);
;     float ps = 0; for (int r = 0; r < 16; ++r) ps += p0[r]; for (int r = 0; r < 16; ++r) ps += p1[r];
;     { auto rr = __builtin_amdgcn_permlane32_swap(__float_as_uint(ps), __float_as_uint(ps), false, false);
;       ps = __uint_as_float(rr[0]) + __uint_as_float(rr[1]); }
;     l_reg = l_reg * alpha + ps;
;     ...
;     PK4(p0, 0, pa0); PK4(p0, 8, pa1); PK4(p1, 0, pa2); PK4(p1, 8, pa3);
;     ...
; }
; template <int KB>
; __device__ __forceinline__ void qkt(f32x16& p0, f32x16& p1, const char* K_lds, int r32, int hi, const bf16x8* qr) {
;     p0 = f32x16{}; p1 = f32x16{};
;     const char* kb[4];
; #pragma unroll
;     for (int dd = 0; dd < 4; ++dd) kb[dd] = K_lds + KB * SHM_K + KSWZ(r32, (dd * 16 + hi * 8) * 2);
; #pragma unroll
;     for (int d0 = 0; d0 < 8; ++d0) { const char* a = kb[d0 & 3] + (d0 >> 2) * 128;
;         bf16x8 b0 = *reinterpret_cast<const bf16x8*>(a);
;         bf16x8 b1 = *reinterpret_cast<const bf16x8*>(a + 32 * 256);
;         p0 = __builtin_amdgcn_mfma_f32_32x32x16_bf16(b0, qr[d0], p0, 0, 0, 0);
;         p1 = __builtin_amdgcn_mfma_f32_32x32x16_bf16(b1, qr[d0], p1, 0, 0, 0); }
; }
	s_waitcnt vmcnt(0)
	ds_read_b128 v[66:69], v169 offset:32768
	ds_read_b128 v[70:73], v169 offset:40960
	ds_read_b128 v[172:175], v193 offset:32768
	ds_read_b128 v[228:231], v193 offset:40960
	s_waitcnt lgkmcnt(3)
	v_mfma_f32_32x32x16_bf16 v[82:97], v[66:69], v[132:135], 0
	v_exp_f32_e32 v198, v198
	v_exp_f32_e32 v201, v201
	v_exp_f32_e32 v214, v204
	v_exp_f32_e32 v205, v205
	v_exp_f32_e32 v206, v206
	s_waitcnt lgkmcnt(2)
	v_mfma_f32_32x32x16_bf16 v[66:81], v[70:73], v[132:135], 0
	v_exp_f32_e32 v207, v207
	v_exp_f32_e32 v181, v181
	v_exp_f32_e32 v215, v226
	v_exp_f32_e32 v216, v227
	v_exp_f32_e32 v180, v180
	s_waitcnt lgkmcnt(1)
	v_mfma_f32_32x32x16_bf16 v[82:97], v[172:175], v[128:131], v[82:97]
	v_exp_f32_e32 v235, v209
	v_exp_f32_e32 v209, v203
	v_add_f32_e32 v203, 0, v148
	v_add_f32_e32 v203, v163, v203
	v_add_f32_e32 v203, v149, v203
	s_waitcnt lgkmcnt(0)
	v_mfma_f32_32x32x16_bf16 v[66:81], v[228:231], v[128:131], v[66:81]
	v_add_f32_e32 v203, v162, v203
	v_add_f32_e32 v203, v150, v203
	v_add_f32_e32 v203, v161, v203
	v_add_f32_e32 v203, v151, v203
	v_add_f32_e32 v203, v160, v203
	ds_read_b128 v[172:175], v194 offset:32768
	ds_read_b128 v[228:231], v194 offset:40960
	s_waitcnt lgkmcnt(1)
	v_mfma_f32_32x32x16_bf16 v[82:97], v[172:175], v[124:127], v[82:97]
	v_add_f32_e32 v203, v152, v203
	v_add_f32_e32 v203, v159, v203
	v_add_f32_e32 v203, v153, v203
	v_add_f32_e32 v203, v158, v203
	v_exp_f32_e32 v234, v208
	s_waitcnt lgkmcnt(0)
	v_mfma_f32_32x32x16_bf16 v[66:81], v[228:231], v[124:127], v[66:81]
	v_add_f32_e32 v203, v154, v203
	v_add_f32_e32 v203, v157, v203
	v_exp_f32_e32 v236, v223
	v_add_f32_e32 v203, v155, v203
	v_exp_f32_e32 v237, v224
	ds_read_b128 v[172:175], v195 offset:32768
	ds_read_b128 v[228:231], v195 offset:40960
	s_waitcnt lgkmcnt(1)
	v_mfma_f32_32x32x16_bf16 v[82:97], v[172:175], v[120:123], v[82:97]
	v_add_f32_e32 v203, v156, v203
	v_exp_f32_e32 v208, v225
	v_add_f32_e32 v203, v234, v203
	v_add_f32_e32 v203, v235, v203
	v_add_f32_e32 v203, v236, v203
	s_waitcnt lgkmcnt(0)
	v_mfma_f32_32x32x16_bf16 v[66:81], v[228:231], v[120:123], v[66:81]
	v_add_f32_e32 v203, v237, v203
	v_add_f32_e32 v203, v208, v203
	v_add_f32_e32 v203, v198, v203
	v_add_f32_e32 v203, v201, v203
	v_add_f32_e32 v203, v209, v203
	ds_read_b128 v[172:175], v169 offset:32896
	ds_read_b128 v[228:231], v169 offset:41088
	s_waitcnt lgkmcnt(1)
	v_mfma_f32_32x32x16_bf16 v[82:97], v[172:175], v[116:119], v[82:97]
	v_add_f32_e32 v203, v214, v203
	v_add_f32_e32 v203, v205, v203
	v_add_f32_e32 v203, v206, v203
	v_add_f32_e32 v203, v207, v203
	v_add_f32_e32 v203, v181, v203
	s_waitcnt lgkmcnt(0)
	v_mfma_f32_32x32x16_bf16 v[66:81], v[228:231], v[116:119], v[66:81]
	v_add_f32_e32 v203, v215, v203
	v_add_f32_e32 v203, v216, v203
	v_add_f32_e32 v203, v180, v203
	v_mov_b32_e32 v204, v203
	v_cvt_pk_bf16_f32 v148, v148, v163
	ds_read_b128 v[172:175], v193 offset:32896
	ds_read_b128 v[228:231], v193 offset:41088
	s_waitcnt lgkmcnt(1)
	v_mfma_f32_32x32x16_bf16 v[82:97], v[172:175], v[112:115], v[82:97]
	v_cvt_pk_bf16_f32 v149, v149, v162
	v_cvt_pk_bf16_f32 v150, v150, v161
	v_cvt_pk_bf16_f32 v151, v151, v160
	v_cvt_pk_bf16_f32 v152, v152, v159
	v_cvt_pk_bf16_f32 v153, v153, v158
	s_waitcnt lgkmcnt(0)
	v_mfma_f32_32x32x16_bf16 v[66:81], v[228:231], v[112:115], v[66:81]
	v_cvt_pk_bf16_f32 v154, v154, v157
	v_cvt_pk_bf16_f32 v155, v155, v156
	v_cvt_pk_bf16_f32 v156, v234, v235
	v_cvt_pk_bf16_f32 v157, v236, v237
	v_cvt_pk_bf16_f32 v158, v208, v198
	ds_read_b128 v[172:175], v194 offset:32896
	ds_read_b128 v[228:231], v194 offset:41088
	s_waitcnt lgkmcnt(1)
	v_mfma_f32_32x32x16_bf16 v[82:97], v[172:175], v[108:111], v[82:97]
	v_cvt_pk_bf16_f32 v159, v201, v209
	v_cvt_pk_bf16_f32 v160, v214, v205
	v_cvt_pk_bf16_f32 v161, v206, v207
	v_cvt_pk_bf16_f32 v162, v181, v215
	v_cvt_pk_bf16_f32 v163, v216, v180
	s_waitcnt lgkmcnt(0)
	v_mfma_f32_32x32x16_bf16 v[66:81], v[228:231], v[108:111], v[66:81]
	s_nop 1
	v_permlane32_swap_b32_e32 v203, v204
	v_permlane32_swap_b32_e32 v148, v150
	v_permlane32_swap_b32_e32 v149, v151
	v_permlane32_swap_b32_e32 v152, v154
	v_permlane32_swap_b32_e32 v153, v155
	ds_read_b128 v[172:175], v195 offset:32896
	ds_read_b128 v[228:231], v195 offset:41088
	s_waitcnt lgkmcnt(1)
	v_mfma_f32_32x32x16_bf16 v[82:97], v[172:175], v[104:107], v[82:97]
	v_permlane32_swap_b32_e32 v156, v158
	v_permlane32_swap_b32_e32 v157, v159
	v_permlane32_swap_b32_e32 v160, v162
	v_permlane32_swap_b32_e32 v161, v163
	s_waitcnt lgkmcnt(0)
	v_mfma_f32_32x32x16_bf16 v[66:81], v[228:231], v[104:107], v[66:81]
	s_cmp_lt_u32 s3, s2
	s_cselect_b64 s[22:23], -1, 0
	s_cmp_ge_u32 s3, s2
	s_cbranch_scc1 .LBB0_97
	v_add_u32_e32 v100, 0x41, v178
	v_add_u32_e32 v102, 0x61, v178
	v_ashrrev_i32_e32 v101, 31, v100
	v_ashrrev_i32_e32 v103, 31, v102
	v_lshlrev_b64 v[140:141], 8, v[100:101]
	v_lshlrev_b64 v[142:143], 8, v[102:103]
	v_lshl_add_u64 v[100:101], v[170:171], 0, v[140:141]
	v_lshl_add_u64 v[136:137], v[170:171], 0, v[142:143]
	v_lshl_add_u64 v[140:141], v[176:177], 0, v[140:141]
	v_lshl_add_u64 v[144:145], v[176:177], 0, v[142:143]
	global_load_dwordx4 v[100:103], v[100:101], off
	s_nop 0
	global_load_dwordx4 v[136:139], v[136:137], off
	s_nop 0
	global_load_dwordx4 v[140:143], v[140:141], off
	s_nop 0
	global_load_dwordx4 v[144:147], v[144:145], off
